# gating MFMA chain: T-fragment LDS reads kept three ahead of the MFMAs in their own registers (counted lgkmcnt), W fragments no longer overwritten
# baseline (speedup 1.0000x reference)
; __device__ __forceinline__ unsigned pk2(float lo, float hi) { return pg8::cvt_pk_bf16(lo, hi); }
; __device__ __forceinline__ float bflo(unsigned w) { return __uint_as_float(w << 16); }
; __device__ __forceinline__ float bfhi(unsigned w) { return __uint_as_float(w & 0xffff0000u); }
; __device__ __forceinline__ void gate_phase(int bx, int G, bool skip_ctx, const bf16* __restrict__ VG, const bf16* __restrict__ U, const float* __restrict__ stats, ...
;     ...
;         f32x16 acc = {};
;         const bf16* trow = T + (db * 32 + r32) * GT_PITCH + hi * 8;
; #pragma unroll
;         for (int ks = 0; ks < 8; ++ks) {
;             const bf16x8 av = *(const bf16x8*)(trow + ks * 16);
;             acc = __builtin_amdgcn_mfma_f32_32x32x16_bf16(av, wcur[ks], acc, 0, 0, 0);
;         }
;         const size_t row = (size_t)chunk * 128 + p;
; #pragma unroll
;         for (int g4 = 0; g4 < 4; ++g4) {
;             const int d0 = db * 32 + 8 * g4 + 4 * hi;
;             u32x2 w;
;             w.x = pk2(bflo(ucur[g4].x) * (acc[4 * g4 + 0] + bias), bfhi(ucur[g4].x) * (acc[4 * g4 + 1] + bias));
;             w.y = pk2(bflo(ucur[g4].y) * (acc[4 * g4 + 2] + bias), bfhi(ucur[g4].y) * (acc[4 * g4 + 3] + bias));
;             *(u32x2*)(MIX + row * 1024 + 512 + h * 64 + d0) = w;
;         }
;         __syncthreads();
;         u = un;
.LBB0_44:
	s_waitcnt lgkmcnt(0)
	s_barrier
	ds_read_b128 v[4:7], v136
	ds_read_b128 v[138:141], v136 offset:32
	ds_read_b128 v[16:19], v136 offset:64
	s_waitcnt lgkmcnt(2)
	v_mfma_f32_32x32x16_bf16 v[0:15], v[4:7], v[0:3], 0
	ds_read_b128 v[20:23], v136 offset:96
	s_ashr_i32 s26, s13, 3
	s_ashr_i32 s27, s26, 31
	s_lshl_b64 s[26:27], s[26:27], 18
	s_lshl_b32 s72, s19, 1
	s_andn2_b64 vcc, exec, s[22:23]
	s_waitcnt lgkmcnt(2)
	v_mfma_f32_32x32x16_bf16 v[0:15], v[138:141], v[60:63], v[0:15]
	ds_read_b128 v[24:27], v136 offset:128
	s_waitcnt lgkmcnt(2)
	v_mfma_f32_32x32x16_bf16 v[0:15], v[16:19], v[64:67], v[0:15]
	ds_read_b128 v[188:191], v136 offset:160
	v_mov_b64_e32 v[64:65], v[76:77]
	v_mov_b64_e32 v[66:67], v[78:79]
	s_waitcnt lgkmcnt(2)
	v_mfma_f32_32x32x16_bf16 v[0:15], v[20:23], v[52:55], v[0:15]
	ds_read_b128 v[192:195], v136 offset:192
	v_mov_b64_e32 v[60:61], v[72:73]
	v_mov_b64_e32 v[62:63], v[74:75]
	s_waitcnt lgkmcnt(2)
	v_mfma_f32_32x32x16_bf16 v[0:15], v[24:27], v[56:59], v[0:15]
	ds_read_b128 v[196:199], v136 offset:224
	v_xor_b32_e32 v136, 0x8000, v136
	v_mov_b64_e32 v[56:57], v[84:85]
	v_mov_b64_e32 v[58:59], v[86:87]
	s_waitcnt lgkmcnt(2)
	v_mfma_f32_32x32x16_bf16 v[0:15], v[188:191], v[48:51], v[0:15]
	v_mov_b64_e32 v[52:53], v[80:81]
	v_mov_b64_e32 v[54:55], v[82:83]
	s_waitcnt lgkmcnt(1)
	v_mfma_f32_32x32x16_bf16 v[0:15], v[192:195], v[44:47], v[0:15]
	v_mov_b64_e32 v[48:49], v[88:89]
	v_mov_b64_e32 v[50:51], v[90:91]
	s_waitcnt lgkmcnt(0)
	v_mfma_f32_32x32x16_bf16 v[0:15], v[196:199], v[40:43], v[0:15]
	v_lshlrev_b32_e32 v42, 16, v124
	v_lshl_add_u64 v[40:41], v[112:113], 0, s[26:27]
	v_lshl_add_u64 v[40:41], v[40:41], 0, s[72:73]
	v_mov_b64_e32 v[44:45], v[92:93]
	v_mov_b64_e32 v[46:47], v[94:95]
	s_nop 10
	v_add_f32_e32 v0, v137, v0
	v_mul_f32_e32 v0, v0, v42
	v_and_b32_e32 v42, 0xffff0000, v124
	v_add_f32_e32 v1, v137, v1
	v_mul_f32_e32 v1, v1, v42
	v_cvt_pk_bf16_f32 v172, v0, v1
	v_lshlrev_b32_e32 v0, 16, v125
	v_add_f32_e32 v1, v137, v2
	v_mul_f32_e32 v0, v1, v0
	v_and_b32_e32 v1, 0xffff0000, v125
	v_add_f32_e32 v2, v137, v3
	v_mul_f32_e32 v1, v2, v1
	v_lshlrev_b32_e32 v2, 16, v122
	v_add_f32_e32 v3, v137, v4
	v_mul_f32_e32 v2, v3, v2
	v_and_b32_e32 v3, 0xffff0000, v122
	v_add_f32_e32 v4, v137, v5
	v_cvt_pk_bf16_f32 v173, v0, v1
	v_lshl_add_u64 v[0:1], v[40:41], 0, v[160:161]
	v_mul_f32_e32 v3, v4, v3
	v_cvt_pk_bf16_f32 v176, v2, v3
	v_lshlrev_b32_e32 v3, 16, v123
	v_add_f32_e32 v4, v137, v6
	v_mul_f32_e32 v3, v4, v3
	v_and_b32_e32 v4, 0xffff0000, v123
	v_add_f32_e32 v5, v137, v7
	v_mul_f32_e32 v4, v5, v4
	v_cvt_pk_bf16_f32 v177, v3, v4
	v_lshlrev_b32_e32 v2, 16, v120
	v_add_f32_e32 v3, v137, v8
	v_mul_f32_e32 v2, v3, v2
	v_and_b32_e32 v3, 0xffff0000, v120
	v_add_f32_e32 v4, v137, v9
	v_mul_f32_e32 v3, v4, v3
	v_cvt_pk_bf16_f32 v174, v2, v3
	v_lshlrev_b32_e32 v3, 16, v121
	v_add_f32_e32 v4, v137, v10
	v_mul_f32_e32 v3, v4, v3
	v_and_b32_e32 v4, 0xffff0000, v121
	v_add_f32_e32 v5, v137, v11
	v_mul_f32_e32 v4, v5, v4
	v_cvt_pk_bf16_f32 v175, v3, v4
	v_lshlrev_b32_e32 v2, 16, v106
	v_add_f32_e32 v3, v137, v12
	v_mul_f32_e32 v2, v3, v2
	v_and_b32_e32 v3, 0xffff0000, v106
	v_add_f32_e32 v4, v137, v13
	v_mul_f32_e32 v3, v4, v3
	v_cvt_pk_bf16_f32 v178, v2, v3
	v_lshlrev_b32_e32 v3, 16, v107
	v_add_f32_e32 v4, v137, v14
	v_mul_f32_e32 v3, v4, v3
	v_and_b32_e32 v4, 0xffff0000, v107
	v_add_f32_e32 v5, v137, v15
	v_mul_f32_e32 v4, v5, v4
	v_cvt_pk_bf16_f32 v179, v3, v4
	s_nop 1
	v_permlane32_swap_b32_e32 v172, v174
	v_permlane32_swap_b32_e32 v173, v175
	v_permlane32_swap_b32_e32 v176, v178
	v_permlane32_swap_b32_e32 v177, v179
	global_store_dwordx4 v[0:1], v[172:175], off offset:1024
	global_store_dwordx4 v[0:1], v[176:179], off offset:1040
	s_waitcnt vmcnt(2)
	v_permlane32_swap_b32_e32 v126, v128
	v_permlane32_swap_b32_e32 v127, v129
	v_permlane32_swap_b32_e32 v130, v132
	v_permlane32_swap_b32_e32 v131, v133
	v_mov_b64_e32 v[0:1], v[68:69]
	v_mov_b64_e32 v[40:41], v[96:97]
	v_mov_b64_e32 v[124:125], v[126:127]
	v_mov_b64_e32 v[122:123], v[130:131]
	v_mov_b64_e32 v[120:121], v[128:129]
	v_mov_b64_e32 v[106:107], v[132:133]
	v_mov_b64_e32 v[2:3], v[70:71]
	v_mov_b64_e32 v[42:43], v[98:99]
	v_xor_b32_e32 v134, 0x8000, v134
	v_xor_b32_e32 v135, 0x8000, v135
	s_cbranch_vccnz .LBB0_51
